# decode compute loop regenerated at the third inlined decode site (dpos 0) as well
# speedup vs baseline: 1.0153x; 1.0010x over previous
.LBB0_737:
	v_add_u32_e32 v16, s58, v182
	ds_read_b128 v[4:7], v16 offset:0
	ds_read_b128 v[194:197], v182 offset:0
	ds_read_b128 v[198:201], v182 offset:18944
	ds_read_b128 v[8:11], v16 offset:32
	ds_read_b128 v[202:205], v182 offset:32
	ds_read_b128 v[206:209], v182 offset:18976
	ds_read_b128 v[12:15], v16 offset:64
	ds_read_b128 v[210:213], v182 offset:64
	ds_read_b128 v[214:217], v182 offset:19008
	s_waitcnt lgkmcnt(7)
	v_mfma_f32_32x32x16_bf16 v[162:177], v[194:197], v[4:7], 0
	ds_read_b128 v[186:189], v16 offset:96
	ds_read_b128 v[234:237], v182 offset:96
	ds_read_b128 v[238:241], v182 offset:19040
	ds_read_b128 v[190:193], v16 offset:128
	ds_read_b128 v[242:245], v182 offset:128
	s_waitcnt lgkmcnt(11)
	v_mfma_f32_32x32x16_bf16 v[146:161], v[198:201], v[4:7], 0
	ds_read_b128 v[246:249], v182 offset:19072
	s_waitcnt lgkmcnt(10)
	v_mfma_f32_32x32x16_bf16 v[162:177], v[202:205], v[8:11], v[162:177]
	ds_read_b128 v[4:7], v16 offset:160
	ds_read_b128 v[194:197], v182 offset:160
	s_waitcnt lgkmcnt(11)
	v_mfma_f32_32x32x16_bf16 v[146:161], v[206:209], v[8:11], v[146:161]
	ds_read_b128 v[198:201], v182 offset:19104
	s_waitcnt lgkmcnt(10)
	v_mfma_f32_32x32x16_bf16 v[162:177], v[210:213], v[12:15], v[162:177]
	ds_read_b128 v[8:11], v16 offset:192
	ds_read_b128 v[202:205], v182 offset:192
	s_waitcnt lgkmcnt(11)
	v_mfma_f32_32x32x16_bf16 v[146:161], v[214:217], v[12:15], v[146:161]
	ds_read_b128 v[206:209], v182 offset:19136
	s_waitcnt lgkmcnt(10)
	v_mfma_f32_32x32x16_bf16 v[162:177], v[234:237], v[186:189], v[162:177]
	ds_read_b128 v[12:15], v16 offset:224
	ds_read_b128 v[210:213], v182 offset:224
	s_waitcnt lgkmcnt(11)
	v_mfma_f32_32x32x16_bf16 v[146:161], v[238:241], v[186:189], v[146:161]
	ds_read_b128 v[214:217], v182 offset:19168
	s_waitcnt lgkmcnt(10)
	v_mfma_f32_32x32x16_bf16 v[162:177], v[242:245], v[190:193], v[162:177]
	ds_read_b128 v[186:189], v16 offset:256
	ds_read_b128 v[234:237], v182 offset:256
	s_waitcnt lgkmcnt(11)
	v_mfma_f32_32x32x16_bf16 v[146:161], v[246:249], v[190:193], v[146:161]
	ds_read_b128 v[238:241], v182 offset:19200
	s_waitcnt lgkmcnt(10)
	v_mfma_f32_32x32x16_bf16 v[162:177], v[194:197], v[4:7], v[162:177]
	ds_read_b128 v[190:193], v16 offset:288
	ds_read_b128 v[242:245], v182 offset:288
	s_waitcnt lgkmcnt(11)
	v_mfma_f32_32x32x16_bf16 v[146:161], v[198:201], v[4:7], v[146:161]
	ds_read_b128 v[246:249], v182 offset:19232
	s_waitcnt lgkmcnt(10)
	v_mfma_f32_32x32x16_bf16 v[162:177], v[202:205], v[8:11], v[162:177]
	ds_read_b128 v[4:7], v16 offset:320
	ds_read_b128 v[194:197], v182 offset:320
	s_waitcnt lgkmcnt(11)
	v_mfma_f32_32x32x16_bf16 v[146:161], v[206:209], v[8:11], v[146:161]
	ds_read_b128 v[198:201], v182 offset:19264
	s_waitcnt lgkmcnt(10)
	v_mfma_f32_32x32x16_bf16 v[162:177], v[210:213], v[12:15], v[162:177]
	ds_read_b128 v[8:11], v16 offset:352
	ds_read_b128 v[202:205], v182 offset:352
	s_waitcnt lgkmcnt(11)
	v_mfma_f32_32x32x16_bf16 v[146:161], v[214:217], v[12:15], v[146:161]
	ds_read_b128 v[206:209], v182 offset:19296
	s_waitcnt lgkmcnt(10)
	v_mfma_f32_32x32x16_bf16 v[162:177], v[234:237], v[186:189], v[162:177]
	ds_read_b128 v[12:15], v16 offset:384
	ds_read_b128 v[210:213], v182 offset:384
	s_waitcnt lgkmcnt(11)
	v_mfma_f32_32x32x16_bf16 v[146:161], v[238:241], v[186:189], v[146:161]
	ds_read_b128 v[214:217], v182 offset:19328
	s_waitcnt lgkmcnt(10)
	v_mfma_f32_32x32x16_bf16 v[162:177], v[242:245], v[190:193], v[162:177]
	ds_read_b128 v[186:189], v16 offset:416
	ds_read_b128 v[234:237], v182 offset:416
	s_waitcnt lgkmcnt(11)
	v_mfma_f32_32x32x16_bf16 v[146:161], v[246:249], v[190:193], v[146:161]
	ds_read_b128 v[238:241], v182 offset:19360
	s_waitcnt lgkmcnt(10)
	v_mfma_f32_32x32x16_bf16 v[162:177], v[194:197], v[4:7], v[162:177]
	ds_read_b128 v[190:193], v16 offset:448
	ds_read_b128 v[242:245], v182 offset:448
	s_waitcnt lgkmcnt(11)
	v_mfma_f32_32x32x16_bf16 v[146:161], v[198:201], v[4:7], v[146:161]
	ds_read_b128 v[246:249], v182 offset:19392
	s_waitcnt lgkmcnt(10)
	v_mfma_f32_32x32x16_bf16 v[162:177], v[202:205], v[8:11], v[162:177]
	ds_read_b128 v[4:7], v16 offset:480
	ds_read_b128 v[194:197], v182 offset:480
	s_waitcnt lgkmcnt(11)
	v_mfma_f32_32x32x16_bf16 v[146:161], v[206:209], v[8:11], v[146:161]
	ds_read_b128 v[198:201], v182 offset:19424
	s_waitcnt lgkmcnt(10)
	v_mfma_f32_32x32x16_bf16 v[162:177], v[210:213], v[12:15], v[162:177]
	ds_read_b128 v[8:11], v16 offset:512
	ds_read_b128 v[202:205], v182 offset:512
	s_waitcnt lgkmcnt(11)
	v_mfma_f32_32x32x16_bf16 v[146:161], v[214:217], v[12:15], v[146:161]
	ds_read_b128 v[206:209], v182 offset:19456
	s_waitcnt lgkmcnt(10)
	v_mfma_f32_32x32x16_bf16 v[162:177], v[234:237], v[186:189], v[162:177]
	ds_read_b128 v[12:15], v16 offset:544
	ds_read_b128 v[210:213], v182 offset:544
	s_waitcnt lgkmcnt(11)
	v_mfma_f32_32x32x16_bf16 v[146:161], v[238:241], v[186:189], v[146:161]
	ds_read_b128 v[214:217], v182 offset:19488
	s_waitcnt lgkmcnt(10)
	v_mfma_f32_32x32x16_bf16 v[162:177], v[242:245], v[190:193], v[162:177]
	s_waitcnt lgkmcnt(9)
	v_mfma_f32_32x32x16_bf16 v[146:161], v[246:249], v[190:193], v[146:161]
	s_waitcnt lgkmcnt(7)
	v_mfma_f32_32x32x16_bf16 v[162:177], v[194:197], v[4:7], v[162:177]
	s_waitcnt lgkmcnt(6)
	v_mfma_f32_32x32x16_bf16 v[146:161], v[198:201], v[4:7], v[146:161]
	s_waitcnt lgkmcnt(4)
	v_mfma_f32_32x32x16_bf16 v[162:177], v[202:205], v[8:11], v[162:177]
	s_waitcnt lgkmcnt(3)
	v_mfma_f32_32x32x16_bf16 v[146:161], v[206:209], v[8:11], v[146:161]
	s_waitcnt lgkmcnt(1)
	v_mfma_f32_32x32x16_bf16 v[162:177], v[210:213], v[12:15], v[162:177]
	s_waitcnt lgkmcnt(0)
	v_mfma_f32_32x32x16_bf16 v[146:161], v[214:217], v[12:15], v[146:161]
	ds_read_b64_tr_b16 v[190:191], v184 offset:0
	ds_read_b64_tr_b16 v[192:193], v184 offset:4736
	ds_read_b64_tr_b16 v[194:195], v184 offset:64
	ds_read_b64_tr_b16 v[196:197], v184 offset:4800
	ds_read_b64_tr_b16 v[198:199], v184 offset:128
	ds_read_b64_tr_b16 v[200:201], v184 offset:4864
	ds_read_b64_tr_b16 v[202:203], v184 offset:192
	ds_read_b64_tr_b16 v[204:205], v184 offset:4928
	ds_read_b64_tr_b16 v[206:207], v184 offset:256
	ds_read_b64_tr_b16 v[208:209], v184 offset:4992
	ds_read_b64_tr_b16 v[210:211], v184 offset:320
	ds_read_b64_tr_b16 v[212:213], v184 offset:5056
	ds_read_b64_tr_b16 v[214:215], v184 offset:384
	ds_read_b64_tr_b16 v[216:217], v184 offset:5120
	v_max3_f32 v2, v162, v146, v163
	v_max3_f32 v17, v147, v164, v148
	v_max3_f32 v2, v2, v165, v149
	v_max3_f32 v17, v17, v166, v150
	v_max3_f32 v2, v2, v167, v151
	v_max3_f32 v17, v17, v168, v152
	v_max3_f32 v2, v2, v169, v153
	v_max3_f32 v17, v17, v170, v154
	v_max3_f32 v2, v2, v171, v155
	v_max3_f32 v17, v17, v172, v156
	v_max3_f32 v2, v2, v173, v157
	v_max3_f32 v17, v17, v174, v158
	v_max3_f32 v2, v2, v175, v159
	v_max3_f32 v17, v17, v176, v160
	v_max3_f32 v2, v2, v17, v177
	v_max_f32_e32 v2, v2, v161
	v_mov_b32_e32 v218, v2
	v_add_f32_e32 v233, 0x41000000, v178
	v_mov_b32_e32 v254, 0
	v_permlane32_swap_b32_e32 v2, v218
	v_max_f32_e32 v2, v2, v218
	v_mul_f32_e32 v2, 0x3e16c740, v2
	v_cmp_gt_f32_e32 vcc, v2, v233
	s_cbranch_vccz .Ldc0_nr0
	v_max_f32_e32 v2, v178, v2
	v_sub_f32_e32 v219, v178, v2
	v_exp_f32_e32 v219, v219
	v_mov_b32_e32 v178, v2
	v_mov_b32_e32 v218, v2
	v_mul_f32_e32 v183, v183, v219
	v_mul_f32_e32 v130, v130, v219
	v_mul_f32_e32 v131, v131, v219
	v_mul_f32_e32 v132, v132, v219
	v_mul_f32_e32 v133, v133, v219
	v_mul_f32_e32 v134, v134, v219
	v_mul_f32_e32 v135, v135, v219
	v_mul_f32_e32 v136, v136, v219
	v_mul_f32_e32 v137, v137, v219
	v_mul_f32_e32 v138, v138, v219
	v_mul_f32_e32 v139, v139, v219
	v_mul_f32_e32 v140, v140, v219
	v_mul_f32_e32 v141, v141, v219
	v_mul_f32_e32 v142, v142, v219
	v_mul_f32_e32 v143, v143, v219
	v_mul_f32_e32 v144, v144, v219
	v_mul_f32_e32 v145, v145, v219
	v_mul_f32_e32 v114, v114, v219
	v_mul_f32_e32 v115, v115, v219
	v_mul_f32_e32 v116, v116, v219
	v_mul_f32_e32 v117, v117, v219
	v_mul_f32_e32 v118, v118, v219
	v_mul_f32_e32 v119, v119, v219
	v_mul_f32_e32 v120, v120, v219
	v_mul_f32_e32 v121, v121, v219
	v_mul_f32_e32 v122, v122, v219
	v_mul_f32_e32 v123, v123, v219
	v_mul_f32_e32 v124, v124, v219
	v_mul_f32_e32 v125, v125, v219
	v_mul_f32_e32 v126, v126, v219
	v_mul_f32_e32 v127, v127, v219
	v_mul_f32_e32 v128, v128, v219
	v_mul_f32_e32 v129, v129, v219
	v_mul_f32_e32 v98, v98, v219
	v_mul_f32_e32 v99, v99, v219
	v_mul_f32_e32 v100, v100, v219
	v_mul_f32_e32 v101, v101, v219
	v_mul_f32_e32 v102, v102, v219
	v_mul_f32_e32 v103, v103, v219
	v_mul_f32_e32 v104, v104, v219
	v_mul_f32_e32 v105, v105, v219
	v_mul_f32_e32 v106, v106, v219
	v_mul_f32_e32 v107, v107, v219
	v_mul_f32_e32 v108, v108, v219
	v_mul_f32_e32 v109, v109, v219
	v_mul_f32_e32 v110, v110, v219
	v_mul_f32_e32 v111, v111, v219
	v_mul_f32_e32 v112, v112, v219
	v_mul_f32_e32 v113, v113, v219
	v_mul_f32_e32 v82, v82, v219
	v_mul_f32_e32 v83, v83, v219
	v_mul_f32_e32 v84, v84, v219
	v_mul_f32_e32 v85, v85, v219
	v_mul_f32_e32 v86, v86, v219
	v_mul_f32_e32 v87, v87, v219
	v_mul_f32_e32 v88, v88, v219
	v_mul_f32_e32 v89, v89, v219
	v_mul_f32_e32 v90, v90, v219
	v_mul_f32_e32 v91, v91, v219
	v_mul_f32_e32 v92, v92, v219
	v_mul_f32_e32 v93, v93, v219
	v_mul_f32_e32 v94, v94, v219
	v_mul_f32_e32 v95, v95, v219
	v_mul_f32_e32 v96, v96, v219
	v_mul_f32_e32 v97, v97, v219
	v_mul_f32_e32 v66, v66, v219
	v_mul_f32_e32 v67, v67, v219
	v_mul_f32_e32 v68, v68, v219
	v_mul_f32_e32 v69, v69, v219
	v_mul_f32_e32 v70, v70, v219
	v_mul_f32_e32 v71, v71, v219
	v_mul_f32_e32 v72, v72, v219
	v_mul_f32_e32 v73, v73, v219
	v_mul_f32_e32 v74, v74, v219
	v_mul_f32_e32 v75, v75, v219
	v_mul_f32_e32 v76, v76, v219
	v_mul_f32_e32 v77, v77, v219
	v_mul_f32_e32 v78, v78, v219
	v_mul_f32_e32 v79, v79, v219
	v_mul_f32_e32 v80, v80, v219
	v_mul_f32_e32 v81, v81, v219
	v_mul_f32_e32 v50, v50, v219
	v_mul_f32_e32 v51, v51, v219
	v_mul_f32_e32 v52, v52, v219
	v_mul_f32_e32 v53, v53, v219
	v_mul_f32_e32 v54, v54, v219
	v_mul_f32_e32 v55, v55, v219
	v_mul_f32_e32 v56, v56, v219
	v_mul_f32_e32 v57, v57, v219
	v_mul_f32_e32 v58, v58, v219
	v_mul_f32_e32 v59, v59, v219
	v_mul_f32_e32 v60, v60, v219
	v_mul_f32_e32 v61, v61, v219
	v_mul_f32_e32 v62, v62, v219
	v_mul_f32_e32 v63, v63, v219
	v_mul_f32_e32 v64, v64, v219
	v_mul_f32_e32 v65, v65, v219
	v_mul_f32_e32 v34, v34, v219
	v_mul_f32_e32 v35, v35, v219
	v_mul_f32_e32 v36, v36, v219
	v_mul_f32_e32 v37, v37, v219
	v_mul_f32_e32 v38, v38, v219
	v_mul_f32_e32 v39, v39, v219
	v_mul_f32_e32 v40, v40, v219
	v_mul_f32_e32 v41, v41, v219
	v_mul_f32_e32 v42, v42, v219
	v_mul_f32_e32 v43, v43, v219
	v_mul_f32_e32 v44, v44, v219
	v_mul_f32_e32 v45, v45, v219
	v_mul_f32_e32 v46, v46, v219
	v_mul_f32_e32 v47, v47, v219
	v_mul_f32_e32 v48, v48, v219
	v_mul_f32_e32 v49, v49, v219
	v_mul_f32_e32 v18, v18, v219
	v_mul_f32_e32 v19, v19, v219
	v_mul_f32_e32 v20, v20, v219
	v_mul_f32_e32 v21, v21, v219
	v_mul_f32_e32 v22, v22, v219
	v_mul_f32_e32 v23, v23, v219
	v_mul_f32_e32 v24, v24, v219
	v_mul_f32_e32 v25, v25, v219
	v_mul_f32_e32 v26, v26, v219
	v_mul_f32_e32 v27, v27, v219
	v_mul_f32_e32 v28, v28, v219
	v_mul_f32_e32 v29, v29, v219
	v_mul_f32_e32 v30, v30, v219
	v_mul_f32_e32 v31, v31, v219
	v_mul_f32_e32 v32, v32, v219
	v_mul_f32_e32 v33, v33, v219
.Ldc0_nr0:
	v_fma_f32 v162, v162, s51, -v178
	v_fma_f32 v146, v146, s51, -v178
	v_fma_f32 v163, v163, s51, -v178
	v_exp_f32_e32 v162, v162
	v_fma_f32 v147, v147, s51, -v178
	v_exp_f32_e32 v146, v146
	v_fma_f32 v164, v164, s51, -v178
	v_exp_f32_e32 v163, v163
	v_fma_f32 v148, v148, s51, -v178
	v_exp_f32_e32 v147, v147
	v_fma_f32 v165, v165, s51, -v178
	v_add_f32_e32 v218, v162, v146
	v_exp_f32_e32 v164, v164
	v_fma_f32 v149, v149, s51, -v178
	v_exp_f32_e32 v148, v148
	v_cvt_pk_bf16_f32 v4, v162, v163
	v_fma_f32 v166, v166, s51, -v178
	v_add_f32_e32 v233, v163, v147
	v_exp_f32_e32 v165, v165
	v_add_f32_e32 v254, v254, v218
	v_cvt_pk_bf16_f32 v12, v146, v147
	v_fma_f32 v150, v150, s51, -v178
	v_exp_f32_e32 v149, v149
	v_fma_f32 v167, v167, s51, -v178
	v_add_f32_e32 v17, v164, v148
	v_exp_f32_e32 v166, v166
	v_add_f32_e32 v254, v254, v233
	v_fma_f32 v151, v151, s51, -v178
	v_exp_f32_e32 v150, v150
	v_cvt_pk_bf16_f32 v5, v164, v165
	v_fma_f32 v168, v168, s51, -v178
	v_add_f32_e32 v219, v165, v149
	v_exp_f32_e32 v167, v167
	v_add_f32_e32 v254, v254, v17
	v_cvt_pk_bf16_f32 v13, v148, v149
	v_fma_f32 v152, v152, s51, -v178
	v_exp_f32_e32 v151, v151
	v_fma_f32 v169, v169, s51, -v178
	v_add_f32_e32 v218, v166, v150
	v_exp_f32_e32 v168, v168
	v_add_f32_e32 v254, v254, v219
	v_fma_f32 v153, v153, s51, -v178
	v_exp_f32_e32 v152, v152
	v_cvt_pk_bf16_f32 v6, v166, v167
	v_fma_f32 v170, v170, s51, -v178
	v_add_f32_e32 v233, v167, v151
	v_exp_f32_e32 v169, v169
	v_add_f32_e32 v254, v254, v218
	v_cvt_pk_bf16_f32 v14, v150, v151
	v_fma_f32 v154, v154, s51, -v178
	v_exp_f32_e32 v153, v153
	v_fma_f32 v171, v171, s51, -v178
	v_add_f32_e32 v17, v168, v152
	v_exp_f32_e32 v170, v170
	v_add_f32_e32 v254, v254, v233
	v_fma_f32 v155, v155, s51, -v178
	v_exp_f32_e32 v154, v154
	v_cvt_pk_bf16_f32 v7, v168, v169
	v_fma_f32 v172, v172, s51, -v178
	v_add_f32_e32 v219, v169, v153
	v_exp_f32_e32 v171, v171
	v_add_f32_e32 v254, v254, v17
	v_cvt_pk_bf16_f32 v15, v152, v153
	v_fma_f32 v156, v156, s51, -v178
	v_exp_f32_e32 v155, v155
	v_fma_f32 v173, v173, s51, -v178
	v_add_f32_e32 v218, v170, v154
	v_exp_f32_e32 v172, v172
	v_add_f32_e32 v254, v254, v219
	v_fma_f32 v157, v157, s51, -v178
	v_exp_f32_e32 v156, v156
	v_cvt_pk_bf16_f32 v8, v170, v171
	v_fma_f32 v174, v174, s51, -v178
	v_add_f32_e32 v233, v171, v155
	v_exp_f32_e32 v173, v173
	v_add_f32_e32 v254, v254, v218
	v_cvt_pk_bf16_f32 v186, v154, v155
	v_fma_f32 v158, v158, s51, -v178
	v_exp_f32_e32 v157, v157
	v_fma_f32 v175, v175, s51, -v178
	v_add_f32_e32 v17, v172, v156
	v_exp_f32_e32 v174, v174
	v_add_f32_e32 v254, v254, v233
	v_fma_f32 v159, v159, s51, -v178
	v_exp_f32_e32 v158, v158
	v_cvt_pk_bf16_f32 v9, v172, v173
	v_fma_f32 v176, v176, s51, -v178
	v_add_f32_e32 v219, v173, v157
	v_exp_f32_e32 v175, v175
	v_add_f32_e32 v254, v254, v17
	v_cvt_pk_bf16_f32 v187, v156, v157
	v_fma_f32 v160, v160, s51, -v178
	v_exp_f32_e32 v159, v159
	v_fma_f32 v177, v177, s51, -v178
	v_add_f32_e32 v218, v174, v158
	v_exp_f32_e32 v176, v176
	v_add_f32_e32 v254, v254, v219
	v_fma_f32 v161, v161, s51, -v178
	v_exp_f32_e32 v160, v160
	v_cvt_pk_bf16_f32 v10, v174, v175
	v_add_f32_e32 v233, v175, v159
	v_exp_f32_e32 v177, v177
	v_add_f32_e32 v254, v254, v218
	v_cvt_pk_bf16_f32 v188, v158, v159
	v_exp_f32_e32 v161, v161
	v_add_f32_e32 v17, v176, v160
	v_add_f32_e32 v254, v254, v233
	v_cvt_pk_bf16_f32 v11, v176, v177
	v_add_f32_e32 v219, v177, v161
	v_add_f32_e32 v254, v254, v17
	v_cvt_pk_bf16_f32 v189, v160, v161
	v_add_f32_e32 v254, v254, v219
	v_add_f32_e32 v183, v183, v254
	s_waitcnt lgkmcnt(12)
	v_mfma_f32_32x32x16_bf16 v[130:145], v[190:193], v[4:7], v[130:145]
	ds_read_b64_tr_b16 v[234:235], v184 offset:448
	ds_read_b64_tr_b16 v[236:237], v184 offset:5184
	s_waitcnt lgkmcnt(12)
	v_mfma_f32_32x32x16_bf16 v[114:129], v[194:197], v[4:7], v[114:129]
	ds_read_b64_tr_b16 v[238:239], v184 offset:9472
	ds_read_b64_tr_b16 v[240:241], v184 offset:14208
	s_waitcnt lgkmcnt(12)
	v_mfma_f32_32x32x16_bf16 v[98:113], v[198:201], v[4:7], v[98:113]
	ds_read_b64_tr_b16 v[242:243], v184 offset:9536
	ds_read_b64_tr_b16 v[244:245], v184 offset:14272
	s_waitcnt lgkmcnt(12)
	v_mfma_f32_32x32x16_bf16 v[82:97], v[202:205], v[4:7], v[82:97]
	ds_read_b64_tr_b16 v[246:247], v184 offset:9600
	ds_read_b64_tr_b16 v[248:249], v184 offset:14336
	s_waitcnt lgkmcnt(12)
	v_mfma_f32_32x32x16_bf16 v[66:81], v[206:209], v[4:7], v[66:81]
	ds_read_b64_tr_b16 v[250:251], v184 offset:9664
	ds_read_b64_tr_b16 v[252:253], v184 offset:14400
	s_waitcnt lgkmcnt(12)
	v_mfma_f32_32x32x16_bf16 v[50:65], v[210:213], v[4:7], v[50:65]
	ds_read_b64_tr_b16 v[190:191], v184 offset:9728
	ds_read_b64_tr_b16 v[192:193], v184 offset:14464
	s_waitcnt lgkmcnt(12)
	v_mfma_f32_32x32x16_bf16 v[34:49], v[214:217], v[4:7], v[34:49]
	ds_read_b64_tr_b16 v[194:195], v184 offset:9792
	ds_read_b64_tr_b16 v[196:197], v184 offset:14528
	s_waitcnt lgkmcnt(12)
	v_mfma_f32_32x32x16_bf16 v[18:33], v[234:237], v[4:7], v[18:33]
	ds_read_b64_tr_b16 v[198:199], v184 offset:9856
	ds_read_b64_tr_b16 v[200:201], v184 offset:14592
	s_waitcnt lgkmcnt(12)
	v_mfma_f32_32x32x16_bf16 v[130:145], v[238:241], v[8:11], v[130:145]
	ds_read_b64_tr_b16 v[202:203], v184 offset:9920
	ds_read_b64_tr_b16 v[204:205], v184 offset:14656
	s_waitcnt lgkmcnt(12)
	v_mfma_f32_32x32x16_bf16 v[114:129], v[242:245], v[8:11], v[114:129]
	ds_read_b64_tr_b16 v[206:207], v184 offset:18944
	ds_read_b64_tr_b16 v[208:209], v184 offset:23680
	s_waitcnt lgkmcnt(12)
	v_mfma_f32_32x32x16_bf16 v[98:113], v[246:249], v[8:11], v[98:113]
	ds_read_b64_tr_b16 v[210:211], v184 offset:19008
	ds_read_b64_tr_b16 v[212:213], v184 offset:23744
	s_waitcnt lgkmcnt(12)
	v_mfma_f32_32x32x16_bf16 v[82:97], v[250:253], v[8:11], v[82:97]
	ds_read_b64_tr_b16 v[214:215], v184 offset:19072
	ds_read_b64_tr_b16 v[216:217], v184 offset:23808
	s_waitcnt lgkmcnt(12)
	v_mfma_f32_32x32x16_bf16 v[66:81], v[190:193], v[8:11], v[66:81]
	ds_read_b64_tr_b16 v[234:235], v184 offset:19136
	ds_read_b64_tr_b16 v[236:237], v184 offset:23872
	s_waitcnt lgkmcnt(12)
	v_mfma_f32_32x32x16_bf16 v[50:65], v[194:197], v[8:11], v[50:65]
	ds_read_b64_tr_b16 v[238:239], v184 offset:19200
	ds_read_b64_tr_b16 v[240:241], v184 offset:23936
	s_waitcnt lgkmcnt(12)
	v_mfma_f32_32x32x16_bf16 v[34:49], v[198:201], v[8:11], v[34:49]
	ds_read_b64_tr_b16 v[242:243], v184 offset:19264
	ds_read_b64_tr_b16 v[244:245], v184 offset:24000
	s_waitcnt lgkmcnt(12)
	v_mfma_f32_32x32x16_bf16 v[18:33], v[202:205], v[8:11], v[18:33]
	ds_read_b64_tr_b16 v[246:247], v184 offset:19328
	ds_read_b64_tr_b16 v[248:249], v184 offset:24064
	s_waitcnt lgkmcnt(12)
	v_mfma_f32_32x32x16_bf16 v[130:145], v[206:209], v[12:15], v[130:145]
	ds_read_b64_tr_b16 v[250:251], v184 offset:19392
	ds_read_b64_tr_b16 v[252:253], v184 offset:24128
	s_waitcnt lgkmcnt(12)
	v_mfma_f32_32x32x16_bf16 v[114:129], v[210:213], v[12:15], v[114:129]
	ds_read_b64_tr_b16 v[190:191], v184 offset:28416
	ds_read_b64_tr_b16 v[192:193], v184 offset:33152
	s_waitcnt lgkmcnt(12)
	v_mfma_f32_32x32x16_bf16 v[98:113], v[214:217], v[12:15], v[98:113]
	ds_read_b64_tr_b16 v[194:195], v184 offset:28480
	ds_read_b64_tr_b16 v[196:197], v184 offset:33216
	s_waitcnt lgkmcnt(12)
	v_mfma_f32_32x32x16_bf16 v[82:97], v[234:237], v[12:15], v[82:97]
	ds_read_b64_tr_b16 v[198:199], v184 offset:28544
	ds_read_b64_tr_b16 v[200:201], v184 offset:33280
	s_waitcnt lgkmcnt(12)
	v_mfma_f32_32x32x16_bf16 v[66:81], v[238:241], v[12:15], v[66:81]
	ds_read_b64_tr_b16 v[202:203], v184 offset:28608
	ds_read_b64_tr_b16 v[204:205], v184 offset:33344
	s_waitcnt lgkmcnt(12)
	v_mfma_f32_32x32x16_bf16 v[50:65], v[242:245], v[12:15], v[50:65]
	ds_read_b64_tr_b16 v[206:207], v184 offset:28672
	ds_read_b64_tr_b16 v[208:209], v184 offset:33408
	s_waitcnt lgkmcnt(12)
	v_mfma_f32_32x32x16_bf16 v[34:49], v[246:249], v[12:15], v[34:49]
	ds_read_b64_tr_b16 v[210:211], v184 offset:28736
	ds_read_b64_tr_b16 v[212:213], v184 offset:33472
	s_waitcnt lgkmcnt(12)
	v_mfma_f32_32x32x16_bf16 v[18:33], v[250:253], v[12:15], v[18:33]
	ds_read_b64_tr_b16 v[214:215], v184 offset:28800
	ds_read_b64_tr_b16 v[216:217], v184 offset:33536
	s_waitcnt lgkmcnt(12)
	v_mfma_f32_32x32x16_bf16 v[130:145], v[190:193], v[186:189], v[130:145]
	ds_read_b64_tr_b16 v[234:235], v184 offset:28864
	ds_read_b64_tr_b16 v[236:237], v184 offset:33600
	s_waitcnt lgkmcnt(12)
	v_mfma_f32_32x32x16_bf16 v[114:129], v[194:197], v[186:189], v[114:129]
	s_waitcnt lgkmcnt(10)
	v_mfma_f32_32x32x16_bf16 v[98:113], v[198:201], v[186:189], v[98:113]
	s_waitcnt lgkmcnt(8)
	v_mfma_f32_32x32x16_bf16 v[82:97], v[202:205], v[186:189], v[82:97]
	s_waitcnt lgkmcnt(6)
	v_mfma_f32_32x32x16_bf16 v[66:81], v[206:209], v[186:189], v[66:81]
	s_waitcnt lgkmcnt(4)
	v_mfma_f32_32x32x16_bf16 v[50:65], v[210:213], v[186:189], v[50:65]
	s_waitcnt lgkmcnt(2)
	v_mfma_f32_32x32x16_bf16 v[34:49], v[214:217], v[186:189], v[34:49]
	s_waitcnt lgkmcnt(0)
	v_mfma_f32_32x32x16_bf16 v[18:33], v[234:237], v[186:189], v[18:33]
	s_waitcnt lgkmcnt(0)
	s_barrier
	ds_read_b128 v[4:7], v16 offset:0
	ds_read_b128 v[194:197], v182 offset:37888
	ds_read_b128 v[198:201], v182 offset:56832
	ds_read_b128 v[8:11], v16 offset:32
	ds_read_b128 v[202:205], v182 offset:37920
	ds_read_b128 v[206:209], v182 offset:56864
	ds_read_b128 v[12:15], v16 offset:64
	ds_read_b128 v[210:213], v182 offset:37952
	ds_read_b128 v[214:217], v182 offset:56896
	s_waitcnt lgkmcnt(7)
	v_mfma_f32_32x32x16_bf16 v[162:177], v[194:197], v[4:7], 0
	ds_read_b128 v[186:189], v16 offset:96
	ds_read_b128 v[234:237], v182 offset:37984
	ds_read_b128 v[238:241], v182 offset:56928
	ds_read_b128 v[190:193], v16 offset:128
	ds_read_b128 v[242:245], v182 offset:38016
	s_waitcnt lgkmcnt(11)
	v_mfma_f32_32x32x16_bf16 v[146:161], v[198:201], v[4:7], 0
	ds_read_b128 v[246:249], v182 offset:56960
	s_waitcnt lgkmcnt(10)
	v_mfma_f32_32x32x16_bf16 v[162:177], v[202:205], v[8:11], v[162:177]
	ds_read_b128 v[4:7], v16 offset:160
	ds_read_b128 v[194:197], v182 offset:38048
	s_waitcnt lgkmcnt(11)
	v_mfma_f32_32x32x16_bf16 v[146:161], v[206:209], v[8:11], v[146:161]
	ds_read_b128 v[198:201], v182 offset:56992
	s_waitcnt lgkmcnt(10)
	v_mfma_f32_32x32x16_bf16 v[162:177], v[210:213], v[12:15], v[162:177]
	ds_read_b128 v[8:11], v16 offset:192
	ds_read_b128 v[202:205], v182 offset:38080
	s_waitcnt lgkmcnt(11)
	v_mfma_f32_32x32x16_bf16 v[146:161], v[214:217], v[12:15], v[146:161]
	ds_read_b128 v[206:209], v182 offset:57024
	s_waitcnt lgkmcnt(10)
	v_mfma_f32_32x32x16_bf16 v[162:177], v[234:237], v[186:189], v[162:177]
	ds_read_b128 v[12:15], v16 offset:224
	ds_read_b128 v[210:213], v182 offset:38112
	s_waitcnt lgkmcnt(11)
	v_mfma_f32_32x32x16_bf16 v[146:161], v[238:241], v[186:189], v[146:161]
	ds_read_b128 v[214:217], v182 offset:57056
	s_waitcnt lgkmcnt(10)
	v_mfma_f32_32x32x16_bf16 v[162:177], v[242:245], v[190:193], v[162:177]
	ds_read_b128 v[186:189], v16 offset:256
	ds_read_b128 v[234:237], v182 offset:38144
	s_waitcnt lgkmcnt(11)
	v_mfma_f32_32x32x16_bf16 v[146:161], v[246:249], v[190:193], v[146:161]
	ds_read_b128 v[238:241], v182 offset:57088
	s_waitcnt lgkmcnt(10)
	v_mfma_f32_32x32x16_bf16 v[162:177], v[194:197], v[4:7], v[162:177]
	ds_read_b128 v[190:193], v16 offset:288
	ds_read_b128 v[242:245], v182 offset:38176
	s_waitcnt lgkmcnt(11)
	v_mfma_f32_32x32x16_bf16 v[146:161], v[198:201], v[4:7], v[146:161]
	ds_read_b128 v[246:249], v182 offset:57120
	s_waitcnt lgkmcnt(10)
	v_mfma_f32_32x32x16_bf16 v[162:177], v[202:205], v[8:11], v[162:177]
	ds_read_b128 v[4:7], v16 offset:320
	ds_read_b128 v[194:197], v182 offset:38208
	s_waitcnt lgkmcnt(11)
	v_mfma_f32_32x32x16_bf16 v[146:161], v[206:209], v[8:11], v[146:161]
	ds_read_b128 v[198:201], v182 offset:57152
	s_waitcnt lgkmcnt(10)
	v_mfma_f32_32x32x16_bf16 v[162:177], v[210:213], v[12:15], v[162:177]
	ds_read_b128 v[8:11], v16 offset:352
	ds_read_b128 v[202:205], v182 offset:38240
	s_waitcnt lgkmcnt(11)
	v_mfma_f32_32x32x16_bf16 v[146:161], v[214:217], v[12:15], v[146:161]
	ds_read_b128 v[206:209], v182 offset:57184
	s_waitcnt lgkmcnt(10)
	v_mfma_f32_32x32x16_bf16 v[162:177], v[234:237], v[186:189], v[162:177]
	ds_read_b128 v[12:15], v16 offset:384
	ds_read_b128 v[210:213], v182 offset:38272
	s_waitcnt lgkmcnt(11)
	v_mfma_f32_32x32x16_bf16 v[146:161], v[238:241], v[186:189], v[146:161]
	ds_read_b128 v[214:217], v182 offset:57216
	s_waitcnt lgkmcnt(10)
	v_mfma_f32_32x32x16_bf16 v[162:177], v[242:245], v[190:193], v[162:177]
	ds_read_b128 v[186:189], v16 offset:416
	ds_read_b128 v[234:237], v182 offset:38304
	s_waitcnt lgkmcnt(11)
	v_mfma_f32_32x32x16_bf16 v[146:161], v[246:249], v[190:193], v[146:161]
	ds_read_b128 v[238:241], v182 offset:57248
	s_waitcnt lgkmcnt(10)
	v_mfma_f32_32x32x16_bf16 v[162:177], v[194:197], v[4:7], v[162:177]
	ds_read_b128 v[190:193], v16 offset:448
	ds_read_b128 v[242:245], v182 offset:38336
	s_waitcnt lgkmcnt(11)
	v_mfma_f32_32x32x16_bf16 v[146:161], v[198:201], v[4:7], v[146:161]
	ds_read_b128 v[246:249], v182 offset:57280
	s_waitcnt lgkmcnt(10)
	v_mfma_f32_32x32x16_bf16 v[162:177], v[202:205], v[8:11], v[162:177]
	ds_read_b128 v[4:7], v16 offset:480
	ds_read_b128 v[194:197], v182 offset:38368
	s_waitcnt lgkmcnt(11)
	v_mfma_f32_32x32x16_bf16 v[146:161], v[206:209], v[8:11], v[146:161]
	ds_read_b128 v[198:201], v182 offset:57312
	s_waitcnt lgkmcnt(10)
	v_mfma_f32_32x32x16_bf16 v[162:177], v[210:213], v[12:15], v[162:177]
	ds_read_b128 v[8:11], v16 offset:512
	ds_read_b128 v[202:205], v182 offset:38400
	s_waitcnt lgkmcnt(11)
	v_mfma_f32_32x32x16_bf16 v[146:161], v[214:217], v[12:15], v[146:161]
	ds_read_b128 v[206:209], v182 offset:57344
	s_waitcnt lgkmcnt(10)
	v_mfma_f32_32x32x16_bf16 v[162:177], v[234:237], v[186:189], v[162:177]
	ds_read_b128 v[12:15], v16 offset:544
	ds_read_b128 v[210:213], v182 offset:38432
	s_waitcnt lgkmcnt(11)
	v_mfma_f32_32x32x16_bf16 v[146:161], v[238:241], v[186:189], v[146:161]
	ds_read_b128 v[214:217], v182 offset:57376
	s_waitcnt lgkmcnt(10)
	v_mfma_f32_32x32x16_bf16 v[162:177], v[242:245], v[190:193], v[162:177]
	s_waitcnt lgkmcnt(9)
	v_mfma_f32_32x32x16_bf16 v[146:161], v[246:249], v[190:193], v[146:161]
	s_waitcnt lgkmcnt(7)
	v_mfma_f32_32x32x16_bf16 v[162:177], v[194:197], v[4:7], v[162:177]
	s_waitcnt lgkmcnt(6)
	v_mfma_f32_32x32x16_bf16 v[146:161], v[198:201], v[4:7], v[146:161]
	s_waitcnt lgkmcnt(4)
	v_mfma_f32_32x32x16_bf16 v[162:177], v[202:205], v[8:11], v[162:177]
	s_waitcnt lgkmcnt(3)
	v_mfma_f32_32x32x16_bf16 v[146:161], v[206:209], v[8:11], v[146:161]
	s_waitcnt lgkmcnt(1)
	v_mfma_f32_32x32x16_bf16 v[162:177], v[210:213], v[12:15], v[162:177]
	s_waitcnt lgkmcnt(0)
	v_mfma_f32_32x32x16_bf16 v[146:161], v[214:217], v[12:15], v[146:161]
	ds_read_b64_tr_b16 v[190:191], v185 offset:0
	ds_read_b64_tr_b16 v[192:193], v185 offset:4736
	ds_read_b64_tr_b16 v[194:195], v185 offset:64
	ds_read_b64_tr_b16 v[196:197], v185 offset:4800
	ds_read_b64_tr_b16 v[198:199], v185 offset:128
	ds_read_b64_tr_b16 v[200:201], v185 offset:4864
	ds_read_b64_tr_b16 v[202:203], v185 offset:192
	ds_read_b64_tr_b16 v[204:205], v185 offset:4928
	ds_read_b64_tr_b16 v[206:207], v185 offset:256
	ds_read_b64_tr_b16 v[208:209], v185 offset:4992
	ds_read_b64_tr_b16 v[210:211], v185 offset:320
	ds_read_b64_tr_b16 v[212:213], v185 offset:5056
	ds_read_b64_tr_b16 v[214:215], v185 offset:384
	ds_read_b64_tr_b16 v[216:217], v185 offset:5120
	v_max3_f32 v2, v162, v146, v163
	v_max3_f32 v17, v147, v164, v148
	v_max3_f32 v2, v2, v165, v149
	v_max3_f32 v17, v17, v166, v150
	v_max3_f32 v2, v2, v167, v151
	v_max3_f32 v17, v17, v168, v152
	v_max3_f32 v2, v2, v169, v153
	v_max3_f32 v17, v17, v170, v154
	v_max3_f32 v2, v2, v171, v155
	v_max3_f32 v17, v17, v172, v156
	v_max3_f32 v2, v2, v173, v157
	v_max3_f32 v17, v17, v174, v158
	v_max3_f32 v2, v2, v175, v159
	v_max3_f32 v17, v17, v176, v160
	v_max3_f32 v2, v2, v17, v177
	v_max_f32_e32 v2, v2, v161
	v_mov_b32_e32 v218, v2
	v_add_f32_e32 v233, 0x41000000, v178
	v_mov_b32_e32 v254, 0
	v_permlane32_swap_b32_e32 v2, v218
	v_max_f32_e32 v2, v2, v218
	v_mul_f32_e32 v2, 0x3e16c740, v2
	v_cmp_gt_f32_e32 vcc, v2, v233
	s_cbranch_vccz .Ldc0_nr1
	v_max_f32_e32 v2, v178, v2
	v_sub_f32_e32 v219, v178, v2
	v_exp_f32_e32 v219, v219
	v_mov_b32_e32 v178, v2
	v_mov_b32_e32 v218, v2
	v_mul_f32_e32 v183, v183, v219
	v_mul_f32_e32 v130, v130, v219
	v_mul_f32_e32 v131, v131, v219
	v_mul_f32_e32 v132, v132, v219
	v_mul_f32_e32 v133, v133, v219
	v_mul_f32_e32 v134, v134, v219
	v_mul_f32_e32 v135, v135, v219
	v_mul_f32_e32 v136, v136, v219
	v_mul_f32_e32 v137, v137, v219
	v_mul_f32_e32 v138, v138, v219
	v_mul_f32_e32 v139, v139, v219
	v_mul_f32_e32 v140, v140, v219
	v_mul_f32_e32 v141, v141, v219
	v_mul_f32_e32 v142, v142, v219
	v_mul_f32_e32 v143, v143, v219
	v_mul_f32_e32 v144, v144, v219
	v_mul_f32_e32 v145, v145, v219
	v_mul_f32_e32 v114, v114, v219
	v_mul_f32_e32 v115, v115, v219
	v_mul_f32_e32 v116, v116, v219
	v_mul_f32_e32 v117, v117, v219
	v_mul_f32_e32 v118, v118, v219
	v_mul_f32_e32 v119, v119, v219
	v_mul_f32_e32 v120, v120, v219
	v_mul_f32_e32 v121, v121, v219
	v_mul_f32_e32 v122, v122, v219
	v_mul_f32_e32 v123, v123, v219
	v_mul_f32_e32 v124, v124, v219
	v_mul_f32_e32 v125, v125, v219
	v_mul_f32_e32 v126, v126, v219
	v_mul_f32_e32 v127, v127, v219
	v_mul_f32_e32 v128, v128, v219
	v_mul_f32_e32 v129, v129, v219
	v_mul_f32_e32 v98, v98, v219
	v_mul_f32_e32 v99, v99, v219
	v_mul_f32_e32 v100, v100, v219
	v_mul_f32_e32 v101, v101, v219
	v_mul_f32_e32 v102, v102, v219
	v_mul_f32_e32 v103, v103, v219
	v_mul_f32_e32 v104, v104, v219
	v_mul_f32_e32 v105, v105, v219
	v_mul_f32_e32 v106, v106, v219
	v_mul_f32_e32 v107, v107, v219
	v_mul_f32_e32 v108, v108, v219
	v_mul_f32_e32 v109, v109, v219
	v_mul_f32_e32 v110, v110, v219
	v_mul_f32_e32 v111, v111, v219
	v_mul_f32_e32 v112, v112, v219
	v_mul_f32_e32 v113, v113, v219
	v_mul_f32_e32 v82, v82, v219
	v_mul_f32_e32 v83, v83, v219
	v_mul_f32_e32 v84, v84, v219
	v_mul_f32_e32 v85, v85, v219
	v_mul_f32_e32 v86, v86, v219
	v_mul_f32_e32 v87, v87, v219
	v_mul_f32_e32 v88, v88, v219
	v_mul_f32_e32 v89, v89, v219
	v_mul_f32_e32 v90, v90, v219
	v_mul_f32_e32 v91, v91, v219
	v_mul_f32_e32 v92, v92, v219
	v_mul_f32_e32 v93, v93, v219
	v_mul_f32_e32 v94, v94, v219
	v_mul_f32_e32 v95, v95, v219
	v_mul_f32_e32 v96, v96, v219
	v_mul_f32_e32 v97, v97, v219
	v_mul_f32_e32 v66, v66, v219
	v_mul_f32_e32 v67, v67, v219
	v_mul_f32_e32 v68, v68, v219
	v_mul_f32_e32 v69, v69, v219
	v_mul_f32_e32 v70, v70, v219
	v_mul_f32_e32 v71, v71, v219
	v_mul_f32_e32 v72, v72, v219
	v_mul_f32_e32 v73, v73, v219
	v_mul_f32_e32 v74, v74, v219
	v_mul_f32_e32 v75, v75, v219
	v_mul_f32_e32 v76, v76, v219
	v_mul_f32_e32 v77, v77, v219
	v_mul_f32_e32 v78, v78, v219
	v_mul_f32_e32 v79, v79, v219
	v_mul_f32_e32 v80, v80, v219
	v_mul_f32_e32 v81, v81, v219
	v_mul_f32_e32 v50, v50, v219
	v_mul_f32_e32 v51, v51, v219
	v_mul_f32_e32 v52, v52, v219
	v_mul_f32_e32 v53, v53, v219
	v_mul_f32_e32 v54, v54, v219
	v_mul_f32_e32 v55, v55, v219
	v_mul_f32_e32 v56, v56, v219
	v_mul_f32_e32 v57, v57, v219
	v_mul_f32_e32 v58, v58, v219
	v_mul_f32_e32 v59, v59, v219
	v_mul_f32_e32 v60, v60, v219
	v_mul_f32_e32 v61, v61, v219
	v_mul_f32_e32 v62, v62, v219
	v_mul_f32_e32 v63, v63, v219
	v_mul_f32_e32 v64, v64, v219
	v_mul_f32_e32 v65, v65, v219
	v_mul_f32_e32 v34, v34, v219
	v_mul_f32_e32 v35, v35, v219
	v_mul_f32_e32 v36, v36, v219
	v_mul_f32_e32 v37, v37, v219
	v_mul_f32_e32 v38, v38, v219
	v_mul_f32_e32 v39, v39, v219
	v_mul_f32_e32 v40, v40, v219
	v_mul_f32_e32 v41, v41, v219
	v_mul_f32_e32 v42, v42, v219
	v_mul_f32_e32 v43, v43, v219
	v_mul_f32_e32 v44, v44, v219
	v_mul_f32_e32 v45, v45, v219
	v_mul_f32_e32 v46, v46, v219
	v_mul_f32_e32 v47, v47, v219
	v_mul_f32_e32 v48, v48, v219
	v_mul_f32_e32 v49, v49, v219
	v_mul_f32_e32 v18, v18, v219
	v_mul_f32_e32 v19, v19, v219
	v_mul_f32_e32 v20, v20, v219
	v_mul_f32_e32 v21, v21, v219
	v_mul_f32_e32 v22, v22, v219
	v_mul_f32_e32 v23, v23, v219
	v_mul_f32_e32 v24, v24, v219
	v_mul_f32_e32 v25, v25, v219
	v_mul_f32_e32 v26, v26, v219
	v_mul_f32_e32 v27, v27, v219
	v_mul_f32_e32 v28, v28, v219
	v_mul_f32_e32 v29, v29, v219
	v_mul_f32_e32 v30, v30, v219
	v_mul_f32_e32 v31, v31, v219
	v_mul_f32_e32 v32, v32, v219
	v_mul_f32_e32 v33, v33, v219
.Ldc0_nr1:
	v_fma_f32 v162, v162, s51, -v178
	v_fma_f32 v146, v146, s51, -v178
	v_fma_f32 v163, v163, s51, -v178
	v_exp_f32_e32 v162, v162
	v_fma_f32 v147, v147, s51, -v178
	v_exp_f32_e32 v146, v146
	v_fma_f32 v164, v164, s51, -v178
	v_exp_f32_e32 v163, v163
	v_fma_f32 v148, v148, s51, -v178
	v_exp_f32_e32 v147, v147
	v_fma_f32 v165, v165, s51, -v178
	v_add_f32_e32 v218, v162, v146
	v_exp_f32_e32 v164, v164
	v_fma_f32 v149, v149, s51, -v178
	v_exp_f32_e32 v148, v148
	v_cvt_pk_bf16_f32 v4, v162, v163
	v_fma_f32 v166, v166, s51, -v178
	v_add_f32_e32 v233, v163, v147
	v_exp_f32_e32 v165, v165
	v_add_f32_e32 v254, v254, v218
	v_cvt_pk_bf16_f32 v12, v146, v147
	v_fma_f32 v150, v150, s51, -v178
	v_exp_f32_e32 v149, v149
	v_fma_f32 v167, v167, s51, -v178
	v_add_f32_e32 v17, v164, v148
	v_exp_f32_e32 v166, v166
	v_add_f32_e32 v254, v254, v233
	v_fma_f32 v151, v151, s51, -v178
	v_exp_f32_e32 v150, v150
	v_cvt_pk_bf16_f32 v5, v164, v165
	v_fma_f32 v168, v168, s51, -v178
	v_add_f32_e32 v219, v165, v149
	v_exp_f32_e32 v167, v167
	v_add_f32_e32 v254, v254, v17
	v_cvt_pk_bf16_f32 v13, v148, v149
	v_fma_f32 v152, v152, s51, -v178
	v_exp_f32_e32 v151, v151
	v_fma_f32 v169, v169, s51, -v178
	v_add_f32_e32 v218, v166, v150
	v_exp_f32_e32 v168, v168
	v_add_f32_e32 v254, v254, v219
	v_fma_f32 v153, v153, s51, -v178
	v_exp_f32_e32 v152, v152
	v_cvt_pk_bf16_f32 v6, v166, v167
	v_fma_f32 v170, v170, s51, -v178
	v_add_f32_e32 v233, v167, v151
	v_exp_f32_e32 v169, v169
	v_add_f32_e32 v254, v254, v218
	v_cvt_pk_bf16_f32 v14, v150, v151
	v_fma_f32 v154, v154, s51, -v178
	v_exp_f32_e32 v153, v153
	v_fma_f32 v171, v171, s51, -v178
	v_add_f32_e32 v17, v168, v152
	v_exp_f32_e32 v170, v170
	v_add_f32_e32 v254, v254, v233
	v_fma_f32 v155, v155, s51, -v178
	v_exp_f32_e32 v154, v154
	v_cvt_pk_bf16_f32 v7, v168, v169
	v_fma_f32 v172, v172, s51, -v178
	v_add_f32_e32 v219, v169, v153
	v_exp_f32_e32 v171, v171
	v_add_f32_e32 v254, v254, v17
	v_cvt_pk_bf16_f32 v15, v152, v153
	v_fma_f32 v156, v156, s51, -v178
	v_exp_f32_e32 v155, v155
	v_fma_f32 v173, v173, s51, -v178
	v_add_f32_e32 v218, v170, v154
	v_exp_f32_e32 v172, v172
	v_add_f32_e32 v254, v254, v219
	v_fma_f32 v157, v157, s51, -v178
	v_exp_f32_e32 v156, v156
	v_cvt_pk_bf16_f32 v8, v170, v171
	v_fma_f32 v174, v174, s51, -v178
	v_add_f32_e32 v233, v171, v155
	v_exp_f32_e32 v173, v173
	v_add_f32_e32 v254, v254, v218
	v_cvt_pk_bf16_f32 v186, v154, v155
	v_fma_f32 v158, v158, s51, -v178
	v_exp_f32_e32 v157, v157
	v_fma_f32 v175, v175, s51, -v178
	v_add_f32_e32 v17, v172, v156
	v_exp_f32_e32 v174, v174
	v_add_f32_e32 v254, v254, v233
	v_fma_f32 v159, v159, s51, -v178
	v_exp_f32_e32 v158, v158
	v_cvt_pk_bf16_f32 v9, v172, v173
	v_fma_f32 v176, v176, s51, -v178
	v_add_f32_e32 v219, v173, v157
	v_exp_f32_e32 v175, v175
	v_add_f32_e32 v254, v254, v17
	v_cvt_pk_bf16_f32 v187, v156, v157
	v_fma_f32 v160, v160, s51, -v178
	v_exp_f32_e32 v159, v159
	v_fma_f32 v177, v177, s51, -v178
	v_add_f32_e32 v218, v174, v158
	v_exp_f32_e32 v176, v176
	v_add_f32_e32 v254, v254, v219
	v_fma_f32 v161, v161, s51, -v178
	v_exp_f32_e32 v160, v160
	v_cvt_pk_bf16_f32 v10, v174, v175
	v_add_f32_e32 v233, v175, v159
	v_exp_f32_e32 v177, v177
	v_add_f32_e32 v254, v254, v218
	v_cvt_pk_bf16_f32 v188, v158, v159
	v_exp_f32_e32 v161, v161
	v_add_f32_e32 v17, v176, v160
	v_add_f32_e32 v254, v254, v233
	v_cvt_pk_bf16_f32 v11, v176, v177
	v_add_f32_e32 v219, v177, v161
	v_add_f32_e32 v254, v254, v17
	v_cvt_pk_bf16_f32 v189, v160, v161
	v_add_f32_e32 v254, v254, v219
	v_add_f32_e32 v183, v183, v254
	s_waitcnt lgkmcnt(12)
	v_mfma_f32_32x32x16_bf16 v[130:145], v[190:193], v[4:7], v[130:145]
	ds_read_b64_tr_b16 v[234:235], v185 offset:448
	ds_read_b64_tr_b16 v[236:237], v185 offset:5184
	s_waitcnt lgkmcnt(12)
	v_mfma_f32_32x32x16_bf16 v[114:129], v[194:197], v[4:7], v[114:129]
	ds_read_b64_tr_b16 v[238:239], v185 offset:9472
	ds_read_b64_tr_b16 v[240:241], v185 offset:14208
	s_waitcnt lgkmcnt(12)
	v_mfma_f32_32x32x16_bf16 v[98:113], v[198:201], v[4:7], v[98:113]
	ds_read_b64_tr_b16 v[242:243], v185 offset:9536
	ds_read_b64_tr_b16 v[244:245], v185 offset:14272
	s_waitcnt lgkmcnt(12)
	v_mfma_f32_32x32x16_bf16 v[82:97], v[202:205], v[4:7], v[82:97]
	ds_read_b64_tr_b16 v[246:247], v185 offset:9600
	ds_read_b64_tr_b16 v[248:249], v185 offset:14336
	s_waitcnt lgkmcnt(12)
	v_mfma_f32_32x32x16_bf16 v[66:81], v[206:209], v[4:7], v[66:81]
	ds_read_b64_tr_b16 v[250:251], v185 offset:9664
	ds_read_b64_tr_b16 v[252:253], v185 offset:14400
	s_waitcnt lgkmcnt(12)
	v_mfma_f32_32x32x16_bf16 v[50:65], v[210:213], v[4:7], v[50:65]
	ds_read_b64_tr_b16 v[190:191], v185 offset:9728
	ds_read_b64_tr_b16 v[192:193], v185 offset:14464
	s_waitcnt lgkmcnt(12)
	v_mfma_f32_32x32x16_bf16 v[34:49], v[214:217], v[4:7], v[34:49]
	ds_read_b64_tr_b16 v[194:195], v185 offset:9792
	ds_read_b64_tr_b16 v[196:197], v185 offset:14528
	s_waitcnt lgkmcnt(12)
	v_mfma_f32_32x32x16_bf16 v[18:33], v[234:237], v[4:7], v[18:33]
	ds_read_b64_tr_b16 v[198:199], v185 offset:9856
	ds_read_b64_tr_b16 v[200:201], v185 offset:14592
	s_waitcnt lgkmcnt(12)
	v_mfma_f32_32x32x16_bf16 v[130:145], v[238:241], v[8:11], v[130:145]
	ds_read_b64_tr_b16 v[202:203], v185 offset:9920
	ds_read_b64_tr_b16 v[204:205], v185 offset:14656
	s_waitcnt lgkmcnt(12)
	v_mfma_f32_32x32x16_bf16 v[114:129], v[242:245], v[8:11], v[114:129]
	ds_read_b64_tr_b16 v[206:207], v185 offset:18944
	ds_read_b64_tr_b16 v[208:209], v185 offset:23680
	s_waitcnt lgkmcnt(12)
	v_mfma_f32_32x32x16_bf16 v[98:113], v[246:249], v[8:11], v[98:113]
	ds_read_b64_tr_b16 v[210:211], v185 offset:19008
	ds_read_b64_tr_b16 v[212:213], v185 offset:23744
	s_waitcnt lgkmcnt(12)
	v_mfma_f32_32x32x16_bf16 v[82:97], v[250:253], v[8:11], v[82:97]
	ds_read_b64_tr_b16 v[214:215], v185 offset:19072
	ds_read_b64_tr_b16 v[216:217], v185 offset:23808
	s_waitcnt lgkmcnt(12)
	v_mfma_f32_32x32x16_bf16 v[66:81], v[190:193], v[8:11], v[66:81]
	ds_read_b64_tr_b16 v[234:235], v185 offset:19136
	ds_read_b64_tr_b16 v[236:237], v185 offset:23872
	s_waitcnt lgkmcnt(12)
	v_mfma_f32_32x32x16_bf16 v[50:65], v[194:197], v[8:11], v[50:65]
	ds_read_b64_tr_b16 v[238:239], v185 offset:19200
	ds_read_b64_tr_b16 v[240:241], v185 offset:23936
	s_waitcnt lgkmcnt(12)
	v_mfma_f32_32x32x16_bf16 v[34:49], v[198:201], v[8:11], v[34:49]
	ds_read_b64_tr_b16 v[242:243], v185 offset:19264
	ds_read_b64_tr_b16 v[244:245], v185 offset:24000
	s_waitcnt lgkmcnt(12)
	v_mfma_f32_32x32x16_bf16 v[18:33], v[202:205], v[8:11], v[18:33]
	ds_read_b64_tr_b16 v[246:247], v185 offset:19328
	ds_read_b64_tr_b16 v[248:249], v185 offset:24064
	s_waitcnt lgkmcnt(12)
	v_mfma_f32_32x32x16_bf16 v[130:145], v[206:209], v[12:15], v[130:145]
	ds_read_b64_tr_b16 v[250:251], v185 offset:19392
	ds_read_b64_tr_b16 v[252:253], v185 offset:24128
	s_waitcnt lgkmcnt(12)
	v_mfma_f32_32x32x16_bf16 v[114:129], v[210:213], v[12:15], v[114:129]
	ds_read_b64_tr_b16 v[190:191], v185 offset:28416
	ds_read_b64_tr_b16 v[192:193], v185 offset:33152
	s_waitcnt lgkmcnt(12)
	v_mfma_f32_32x32x16_bf16 v[98:113], v[214:217], v[12:15], v[98:113]
	ds_read_b64_tr_b16 v[194:195], v185 offset:28480
	ds_read_b64_tr_b16 v[196:197], v185 offset:33216
	s_waitcnt lgkmcnt(12)
	v_mfma_f32_32x32x16_bf16 v[82:97], v[234:237], v[12:15], v[82:97]
	ds_read_b64_tr_b16 v[198:199], v185 offset:28544
	ds_read_b64_tr_b16 v[200:201], v185 offset:33280
	s_waitcnt lgkmcnt(12)
	v_mfma_f32_32x32x16_bf16 v[66:81], v[238:241], v[12:15], v[66:81]
	ds_read_b64_tr_b16 v[202:203], v185 offset:28608
	ds_read_b64_tr_b16 v[204:205], v185 offset:33344
	s_waitcnt lgkmcnt(12)
	v_mfma_f32_32x32x16_bf16 v[50:65], v[242:245], v[12:15], v[50:65]
	ds_read_b64_tr_b16 v[206:207], v185 offset:28672
	ds_read_b64_tr_b16 v[208:209], v185 offset:33408
	s_waitcnt lgkmcnt(12)
	v_mfma_f32_32x32x16_bf16 v[34:49], v[246:249], v[12:15], v[34:49]
	ds_read_b64_tr_b16 v[210:211], v185 offset:28736
	ds_read_b64_tr_b16 v[212:213], v185 offset:33472
	s_waitcnt lgkmcnt(12)
	v_mfma_f32_32x32x16_bf16 v[18:33], v[250:253], v[12:15], v[18:33]
	ds_read_b64_tr_b16 v[214:215], v185 offset:28800
	ds_read_b64_tr_b16 v[216:217], v185 offset:33536
	s_waitcnt lgkmcnt(12)
	v_mfma_f32_32x32x16_bf16 v[130:145], v[190:193], v[186:189], v[130:145]
	ds_read_b64_tr_b16 v[234:235], v185 offset:28864
	ds_read_b64_tr_b16 v[236:237], v185 offset:33600
	s_waitcnt lgkmcnt(12)
	v_mfma_f32_32x32x16_bf16 v[114:129], v[194:197], v[186:189], v[114:129]
	s_waitcnt lgkmcnt(10)
	v_mfma_f32_32x32x16_bf16 v[98:113], v[198:201], v[186:189], v[98:113]
	s_waitcnt lgkmcnt(8)
	v_mfma_f32_32x32x16_bf16 v[82:97], v[202:205], v[186:189], v[82:97]
	s_waitcnt lgkmcnt(6)
	v_mfma_f32_32x32x16_bf16 v[66:81], v[206:209], v[186:189], v[66:81]
	s_waitcnt lgkmcnt(4)
	v_mfma_f32_32x32x16_bf16 v[50:65], v[210:213], v[186:189], v[50:65]
	s_waitcnt lgkmcnt(2)
	v_mfma_f32_32x32x16_bf16 v[34:49], v[214:217], v[186:189], v[34:49]
	s_waitcnt lgkmcnt(0)
	v_mfma_f32_32x32x16_bf16 v[18:33], v[234:237], v[186:189], v[18:33]
	s_waitcnt lgkmcnt(0)
	s_barrier
	s_add_i32 s22, s22, 2
	s_cmp_gt_u32 s22, 61
	s_cbranch_scc0 .LBB0_737
	s_branch .LBB0_742
